# top-k radix select exits early once exactly 16 keys remain above the candidate
# speedup vs baseline: 1.0291x; 1.0063x over previous
; #define LAS __attribute__((address_space(3)))
; DI void nsa_unit(LAS char* lds, int b, int g, int qb, const bf16* Z, const bf16* KC, const bf16* VC, bf16* On, int tid, int lane, int wave) {
;     ...
;             int cnt = 0;
; #pragma unroll 4
;             for (int m4 = 0; m4 < 16; ++m4) {
;                 const f32x4 vm = *(const LAS f32x4*)(vs + 4 * m4);
; #pragma unroll
;                 for (int e = 0; e < 4; ++e) { const int m = 4 * m4 + e; cnt += (vm[e] > v || (vm[e] == v && m < n)) ? 1 : 0; }
;             }
;             const bool sel = (cnt < 16) && (n <= qb);
;             const unsigned long long mk = __ballot(sel);
.Ltk_vals:
	s_or_b64 exec, exec, s[18:19]
	v_cndmask_b32_e64 v34, 0, v0, s[16:17]
	v_cndmask_b32_e64 v38, 0, v37, s[16:17]
	s_mov_b32 s31, 0
	s_mov_b32 s67, 0
	s_mov_b32 s18, 0
	s_mov_b32 s19, 0
	s_or_b32 s52, s31, 0x40000000
	s_or_b32 s98, s67, 0x40000000
	v_cmp_le_u32_e32 vcc, s52, v34
	v_cmp_le_u32_e64 s[100:101], s98, v38
	s_bcnt1_i32_b64 s51, vcc
	s_bcnt1_i32_b64 s99, s[100:101]
	s_cmp_ge_u32 s51, 16
	s_cselect_b32 s31, s52, s31
	s_cmp_ge_u32 s99, 16
	s_cselect_b32 s67, s98, s67
	s_or_b32 s52, s31, 0x20000000
	s_or_b32 s98, s67, 0x20000000
	v_cmp_le_u32_e32 vcc, s52, v34
	v_cmp_le_u32_e64 s[100:101], s98, v38
	s_bcnt1_i32_b64 s51, vcc
	s_bcnt1_i32_b64 s99, s[100:101]
	s_cmp_ge_u32 s51, 16
	s_cselect_b32 s31, s52, s31
	s_cmp_ge_u32 s99, 16
	s_cselect_b32 s67, s98, s67
	s_or_b32 s52, s31, 0x10000000
	s_or_b32 s98, s67, 0x10000000
	v_cmp_le_u32_e32 vcc, s52, v34
	v_cmp_le_u32_e64 s[100:101], s98, v38
	s_bcnt1_i32_b64 s51, vcc
	s_bcnt1_i32_b64 s99, s[100:101]
	s_cmp_ge_u32 s51, 16
	s_cselect_b32 s31, s52, s31
	s_cmp_ge_u32 s99, 16
	s_cselect_b32 s67, s98, s67
	s_or_b32 s52, s31, 0x8000000
	s_or_b32 s98, s67, 0x8000000
	v_cmp_le_u32_e32 vcc, s52, v34
	v_cmp_le_u32_e64 s[100:101], s98, v38
	s_bcnt1_i32_b64 s51, vcc
	s_bcnt1_i32_b64 s99, s[100:101]
	s_cmp_ge_u32 s51, 16
	s_cselect_b32 s31, s52, s31
	s_cmp_ge_u32 s99, 16
	s_cselect_b32 s67, s98, s67
	s_or_b32 s52, s31, 0x4000000
	s_or_b32 s98, s67, 0x4000000
	v_cmp_le_u32_e32 vcc, s52, v34
	v_cmp_le_u32_e64 s[100:101], s98, v38
	s_bcnt1_i32_b64 s51, vcc
	s_bcnt1_i32_b64 s99, s[100:101]
	s_cmp_ge_u32 s51, 16
	s_cselect_b32 s31, s52, s31
	s_cmp_ge_u32 s99, 16
	s_cselect_b32 s67, s98, s67
	s_or_b32 s52, s31, 0x2000000
	s_or_b32 s98, s67, 0x2000000
	v_cmp_le_u32_e32 vcc, s52, v34
	v_cmp_le_u32_e64 s[100:101], s98, v38
	s_bcnt1_i32_b64 s51, vcc
	s_bcnt1_i32_b64 s99, s[100:101]
	s_cmp_ge_u32 s51, 16
	s_cselect_b32 s31, s52, s31
	s_cmp_ge_u32 s99, 16
	s_cselect_b32 s67, s98, s67
	s_or_b32 s52, s31, 0x1000000
	s_or_b32 s98, s67, 0x1000000
	v_cmp_le_u32_e32 vcc, s52, v34
	v_cmp_le_u32_e64 s[100:101], s98, v38
	s_bcnt1_i32_b64 s51, vcc
	s_bcnt1_i32_b64 s99, s[100:101]
	s_cmp_ge_u32 s51, 16
	s_cselect_b32 s31, s52, s31
	s_cmp_ge_u32 s99, 16
	s_cselect_b32 s67, s98, s67
	s_cmp_eq_u32 s51, 16
	s_cselect_b32 s18, 1, s18
	s_cmp_eq_u32 s99, 16
	s_cselect_b32 s19, 1, s19
	s_and_b32 s20, s18, s19
	s_cbranch_scc1 .Ltk_fin
	s_or_b32 s52, s31, 0x800000
	s_or_b32 s98, s67, 0x800000
	v_cmp_le_u32_e32 vcc, s52, v34
	v_cmp_le_u32_e64 s[100:101], s98, v38
	s_bcnt1_i32_b64 s51, vcc
	s_bcnt1_i32_b64 s99, s[100:101]
	s_cmp_ge_u32 s51, 16
	s_cselect_b32 s31, s52, s31
	s_cmp_ge_u32 s99, 16
	s_cselect_b32 s67, s98, s67
	s_cmp_eq_u32 s51, 16
	s_cselect_b32 s18, 1, s18
	s_cmp_eq_u32 s99, 16
	s_cselect_b32 s19, 1, s19
	s_and_b32 s20, s18, s19
	s_cbranch_scc1 .Ltk_fin
	s_or_b32 s52, s31, 0x400000
	s_or_b32 s98, s67, 0x400000
	v_cmp_le_u32_e32 vcc, s52, v34
	v_cmp_le_u32_e64 s[100:101], s98, v38
	s_bcnt1_i32_b64 s51, vcc
	s_bcnt1_i32_b64 s99, s[100:101]
	s_cmp_ge_u32 s51, 16
	s_cselect_b32 s31, s52, s31
	s_cmp_ge_u32 s99, 16
	s_cselect_b32 s67, s98, s67
	s_cmp_eq_u32 s51, 16
	s_cselect_b32 s18, 1, s18
	s_cmp_eq_u32 s99, 16
	s_cselect_b32 s19, 1, s19
	s_and_b32 s20, s18, s19
	s_cbranch_scc1 .Ltk_fin
	s_or_b32 s52, s31, 0x200000
	s_or_b32 s98, s67, 0x200000
	v_cmp_le_u32_e32 vcc, s52, v34
	v_cmp_le_u32_e64 s[100:101], s98, v38
	s_bcnt1_i32_b64 s51, vcc
	s_bcnt1_i32_b64 s99, s[100:101]
	s_cmp_ge_u32 s51, 16
	s_cselect_b32 s31, s52, s31
	s_cmp_ge_u32 s99, 16
	s_cselect_b32 s67, s98, s67
	s_cmp_eq_u32 s51, 16
	s_cselect_b32 s18, 1, s18
	s_cmp_eq_u32 s99, 16
	s_cselect_b32 s19, 1, s19
	s_and_b32 s20, s18, s19
	s_cbranch_scc1 .Ltk_fin
	s_or_b32 s52, s31, 0x100000
	s_or_b32 s98, s67, 0x100000
	v_cmp_le_u32_e32 vcc, s52, v34
	v_cmp_le_u32_e64 s[100:101], s98, v38
	s_bcnt1_i32_b64 s51, vcc
	s_bcnt1_i32_b64 s99, s[100:101]
	s_cmp_ge_u32 s51, 16
	s_cselect_b32 s31, s52, s31
	s_cmp_ge_u32 s99, 16
	s_cselect_b32 s67, s98, s67
	s_cmp_eq_u32 s51, 16
	s_cselect_b32 s18, 1, s18
	s_cmp_eq_u32 s99, 16
	s_cselect_b32 s19, 1, s19
	s_and_b32 s20, s18, s19
	s_cbranch_scc1 .Ltk_fin
	s_or_b32 s52, s31, 0x80000
	s_or_b32 s98, s67, 0x80000
	v_cmp_le_u32_e32 vcc, s52, v34
	v_cmp_le_u32_e64 s[100:101], s98, v38
	s_bcnt1_i32_b64 s51, vcc
	s_bcnt1_i32_b64 s99, s[100:101]
	s_cmp_ge_u32 s51, 16
	s_cselect_b32 s31, s52, s31
	s_cmp_ge_u32 s99, 16
	s_cselect_b32 s67, s98, s67
	s_cmp_eq_u32 s51, 16
	s_cselect_b32 s18, 1, s18
	s_cmp_eq_u32 s99, 16
	s_cselect_b32 s19, 1, s19
	s_and_b32 s20, s18, s19
	s_cbranch_scc1 .Ltk_fin
	s_or_b32 s52, s31, 0x40000
	s_or_b32 s98, s67, 0x40000
	v_cmp_le_u32_e32 vcc, s52, v34
	v_cmp_le_u32_e64 s[100:101], s98, v38
	s_bcnt1_i32_b64 s51, vcc
	s_bcnt1_i32_b64 s99, s[100:101]
	s_cmp_ge_u32 s51, 16
	s_cselect_b32 s31, s52, s31
	s_cmp_ge_u32 s99, 16
	s_cselect_b32 s67, s98, s67
	s_cmp_eq_u32 s51, 16
	s_cselect_b32 s18, 1, s18
	s_cmp_eq_u32 s99, 16
	s_cselect_b32 s19, 1, s19
	s_and_b32 s20, s18, s19
	s_cbranch_scc1 .Ltk_fin
	s_or_b32 s52, s31, 0x20000
	s_or_b32 s98, s67, 0x20000
	v_cmp_le_u32_e32 vcc, s52, v34
	v_cmp_le_u32_e64 s[100:101], s98, v38
	s_bcnt1_i32_b64 s51, vcc
	s_bcnt1_i32_b64 s99, s[100:101]
	s_cmp_ge_u32 s51, 16
	s_cselect_b32 s31, s52, s31
	s_cmp_ge_u32 s99, 16
	s_cselect_b32 s67, s98, s67
	s_cmp_eq_u32 s51, 16
	s_cselect_b32 s18, 1, s18
	s_cmp_eq_u32 s99, 16
	s_cselect_b32 s19, 1, s19
	s_and_b32 s20, s18, s19
	s_cbranch_scc1 .Ltk_fin
; #define LAS __attribute__((address_space(3)))
; DI void nsa_unit(LAS char* lds, int b, int g, int qb, const bf16* Z, const bf16* KC, const bf16* VC, bf16* On, int tid, int lane, int wave) {
;     ...
;             int cnt = 0;
; #pragma unroll 4
;             for (int m4 = 0; m4 < 16; ++m4) {
;                 const f32x4 vm = *(const LAS f32x4*)(vs + 4 * m4);
; #pragma unroll
;                 for (int e = 0; e < 4; ++e) { const int m = 4 * m4 + e; cnt += (vm[e] > v || (vm[e] == v && m < n)) ? 1 : 0; }
;             }
;             const bool sel = (cnt < 16) && (n <= qb);
;             const unsigned long long mk = __ballot(sel);
	s_or_b32 s52, s31, 0x10000
	s_or_b32 s98, s67, 0x10000
	v_cmp_le_u32_e32 vcc, s52, v34
	v_cmp_le_u32_e64 s[100:101], s98, v38
	s_bcnt1_i32_b64 s51, vcc
	s_bcnt1_i32_b64 s99, s[100:101]
	s_cmp_ge_u32 s51, 16
	s_cselect_b32 s31, s52, s31
	s_cmp_ge_u32 s99, 16
	s_cselect_b32 s67, s98, s67
	s_cmp_eq_u32 s51, 16
	s_cselect_b32 s18, 1, s18
	s_cmp_eq_u32 s99, 16
	s_cselect_b32 s19, 1, s19
	s_and_b32 s20, s18, s19
	s_cbranch_scc1 .Ltk_fin
	s_or_b32 s52, s31, 0x8000
	s_or_b32 s98, s67, 0x8000
	v_cmp_le_u32_e32 vcc, s52, v34
	v_cmp_le_u32_e64 s[100:101], s98, v38
	s_bcnt1_i32_b64 s51, vcc
	s_bcnt1_i32_b64 s99, s[100:101]
	s_cmp_ge_u32 s51, 16
	s_cselect_b32 s31, s52, s31
	s_cmp_ge_u32 s99, 16
	s_cselect_b32 s67, s98, s67
	s_cmp_eq_u32 s51, 16
	s_cselect_b32 s18, 1, s18
	s_cmp_eq_u32 s99, 16
	s_cselect_b32 s19, 1, s19
	s_and_b32 s20, s18, s19
	s_cbranch_scc1 .Ltk_fin
	s_or_b32 s52, s31, 0x4000
	s_or_b32 s98, s67, 0x4000
	v_cmp_le_u32_e32 vcc, s52, v34
	v_cmp_le_u32_e64 s[100:101], s98, v38
	s_bcnt1_i32_b64 s51, vcc
	s_bcnt1_i32_b64 s99, s[100:101]
	s_cmp_ge_u32 s51, 16
	s_cselect_b32 s31, s52, s31
	s_cmp_ge_u32 s99, 16
	s_cselect_b32 s67, s98, s67
	s_cmp_eq_u32 s51, 16
	s_cselect_b32 s18, 1, s18
	s_cmp_eq_u32 s99, 16
	s_cselect_b32 s19, 1, s19
	s_and_b32 s20, s18, s19
	s_cbranch_scc1 .Ltk_fin
	s_or_b32 s52, s31, 0x2000
	s_or_b32 s98, s67, 0x2000
	v_cmp_le_u32_e32 vcc, s52, v34
	v_cmp_le_u32_e64 s[100:101], s98, v38
	s_bcnt1_i32_b64 s51, vcc
	s_bcnt1_i32_b64 s99, s[100:101]
	s_cmp_ge_u32 s51, 16
	s_cselect_b32 s31, s52, s31
	s_cmp_ge_u32 s99, 16
	s_cselect_b32 s67, s98, s67
	s_cmp_eq_u32 s51, 16
	s_cselect_b32 s18, 1, s18
	s_cmp_eq_u32 s99, 16
	s_cselect_b32 s19, 1, s19
	s_and_b32 s20, s18, s19
	s_cbranch_scc1 .Ltk_fin
	s_or_b32 s52, s31, 0x1000
	s_or_b32 s98, s67, 0x1000
	v_cmp_le_u32_e32 vcc, s52, v34
	v_cmp_le_u32_e64 s[100:101], s98, v38
	s_bcnt1_i32_b64 s51, vcc
	s_bcnt1_i32_b64 s99, s[100:101]
	s_cmp_ge_u32 s51, 16
	s_cselect_b32 s31, s52, s31
	s_cmp_ge_u32 s99, 16
	s_cselect_b32 s67, s98, s67
	s_cmp_eq_u32 s51, 16
	s_cselect_b32 s18, 1, s18
	s_cmp_eq_u32 s99, 16
	s_cselect_b32 s19, 1, s19
	s_and_b32 s20, s18, s19
	s_cbranch_scc1 .Ltk_fin
	s_or_b32 s52, s31, 0x800
	s_or_b32 s98, s67, 0x800
	v_cmp_le_u32_e32 vcc, s52, v34
	v_cmp_le_u32_e64 s[100:101], s98, v38
	s_bcnt1_i32_b64 s51, vcc
	s_bcnt1_i32_b64 s99, s[100:101]
	s_cmp_ge_u32 s51, 16
	s_cselect_b32 s31, s52, s31
	s_cmp_ge_u32 s99, 16
	s_cselect_b32 s67, s98, s67
	s_cmp_eq_u32 s51, 16
	s_cselect_b32 s18, 1, s18
	s_cmp_eq_u32 s99, 16
	s_cselect_b32 s19, 1, s19
	s_and_b32 s20, s18, s19
	s_cbranch_scc1 .Ltk_fin
	s_or_b32 s52, s31, 0x400
	s_or_b32 s98, s67, 0x400
	v_cmp_le_u32_e32 vcc, s52, v34
	v_cmp_le_u32_e64 s[100:101], s98, v38
	s_bcnt1_i32_b64 s51, vcc
	s_bcnt1_i32_b64 s99, s[100:101]
	s_cmp_ge_u32 s51, 16
	s_cselect_b32 s31, s52, s31
	s_cmp_ge_u32 s99, 16
	s_cselect_b32 s67, s98, s67
	s_cmp_eq_u32 s51, 16
	s_cselect_b32 s18, 1, s18
	s_cmp_eq_u32 s99, 16
	s_cselect_b32 s19, 1, s19
	s_and_b32 s20, s18, s19
	s_cbranch_scc1 .Ltk_fin
	s_or_b32 s52, s31, 0x200
	s_or_b32 s98, s67, 0x200
	v_cmp_le_u32_e32 vcc, s52, v34
	v_cmp_le_u32_e64 s[100:101], s98, v38
	s_bcnt1_i32_b64 s51, vcc
	s_bcnt1_i32_b64 s99, s[100:101]
	s_cmp_ge_u32 s51, 16
	s_cselect_b32 s31, s52, s31
	s_cmp_ge_u32 s99, 16
	s_cselect_b32 s67, s98, s67
	s_cmp_eq_u32 s51, 16
	s_cselect_b32 s18, 1, s18
	s_cmp_eq_u32 s99, 16
	s_cselect_b32 s19, 1, s19
	s_and_b32 s20, s18, s19
	s_cbranch_scc1 .Ltk_fin
	s_or_b32 s52, s31, 0x100
	s_or_b32 s98, s67, 0x100
	v_cmp_le_u32_e32 vcc, s52, v34
	v_cmp_le_u32_e64 s[100:101], s98, v38
	s_bcnt1_i32_b64 s51, vcc
	s_bcnt1_i32_b64 s99, s[100:101]
	s_cmp_ge_u32 s51, 16
	s_cselect_b32 s31, s52, s31
	s_cmp_ge_u32 s99, 16
	s_cselect_b32 s67, s98, s67
	s_cmp_eq_u32 s51, 16
	s_cselect_b32 s18, 1, s18
	s_cmp_eq_u32 s99, 16
	s_cselect_b32 s19, 1, s19
	s_and_b32 s20, s18, s19
	s_cbranch_scc1 .Ltk_fin
; #define LAS __attribute__((address_space(3)))
; DI void nsa_unit(LAS char* lds, int b, int g, int qb, const bf16* Z, const bf16* KC, const bf16* VC, bf16* On, int tid, int lane, int wave) {
;     ...
;             int cnt = 0;
; #pragma unroll 4
;             for (int m4 = 0; m4 < 16; ++m4) {
;                 const f32x4 vm = *(const LAS f32x4*)(vs + 4 * m4);
; #pragma unroll
;                 for (int e = 0; e < 4; ++e) { const int m = 4 * m4 + e; cnt += (vm[e] > v || (vm[e] == v && m < n)) ? 1 : 0; }
;             }
;             const bool sel = (cnt < 16) && (n <= qb);
;             const unsigned long long mk = __ballot(sel);
;             if (lane == 0) selm[q] = mk;
	s_or_b32 s52, s31, 0x80
	s_or_b32 s98, s67, 0x80
	v_cmp_le_u32_e32 vcc, s52, v34
	v_cmp_le_u32_e64 s[100:101], s98, v38
	s_bcnt1_i32_b64 s51, vcc
	s_bcnt1_i32_b64 s99, s[100:101]
	s_cmp_ge_u32 s51, 16
	s_cselect_b32 s31, s52, s31
	s_cmp_ge_u32 s99, 16
	s_cselect_b32 s67, s98, s67
	s_cmp_eq_u32 s51, 16
	s_cselect_b32 s18, 1, s18
	s_cmp_eq_u32 s99, 16
	s_cselect_b32 s19, 1, s19
	s_and_b32 s20, s18, s19
	s_cbranch_scc1 .Ltk_fin
	s_or_b32 s52, s31, 64
	s_or_b32 s98, s67, 64
	v_cmp_le_u32_e32 vcc, s52, v34
	v_cmp_le_u32_e64 s[100:101], s98, v38
	s_bcnt1_i32_b64 s51, vcc
	s_bcnt1_i32_b64 s99, s[100:101]
	s_cmp_ge_u32 s51, 16
	s_cselect_b32 s31, s52, s31
	s_cmp_ge_u32 s99, 16
	s_cselect_b32 s67, s98, s67
	s_cmp_eq_u32 s51, 16
	s_cselect_b32 s18, 1, s18
	s_cmp_eq_u32 s99, 16
	s_cselect_b32 s19, 1, s19
	s_and_b32 s20, s18, s19
	s_cbranch_scc1 .Ltk_fin
	s_or_b32 s52, s31, 32
	s_or_b32 s98, s67, 32
	v_cmp_le_u32_e32 vcc, s52, v34
	v_cmp_le_u32_e64 s[100:101], s98, v38
	s_bcnt1_i32_b64 s51, vcc
	s_bcnt1_i32_b64 s99, s[100:101]
	s_cmp_ge_u32 s51, 16
	s_cselect_b32 s31, s52, s31
	s_cmp_ge_u32 s99, 16
	s_cselect_b32 s67, s98, s67
	s_cmp_eq_u32 s51, 16
	s_cselect_b32 s18, 1, s18
	s_cmp_eq_u32 s99, 16
	s_cselect_b32 s19, 1, s19
	s_and_b32 s20, s18, s19
	s_cbranch_scc1 .Ltk_fin
	s_or_b32 s52, s31, 16
	s_or_b32 s98, s67, 16
	v_cmp_le_u32_e32 vcc, s52, v34
	v_cmp_le_u32_e64 s[100:101], s98, v38
	s_bcnt1_i32_b64 s51, vcc
	s_bcnt1_i32_b64 s99, s[100:101]
	s_cmp_ge_u32 s51, 16
	s_cselect_b32 s31, s52, s31
	s_cmp_ge_u32 s99, 16
	s_cselect_b32 s67, s98, s67
	s_cmp_eq_u32 s51, 16
	s_cselect_b32 s18, 1, s18
	s_cmp_eq_u32 s99, 16
	s_cselect_b32 s19, 1, s19
	s_and_b32 s20, s18, s19
	s_cbranch_scc1 .Ltk_fin
	s_or_b32 s52, s31, 8
	s_or_b32 s98, s67, 8
	v_cmp_le_u32_e32 vcc, s52, v34
	v_cmp_le_u32_e64 s[100:101], s98, v38
	s_bcnt1_i32_b64 s51, vcc
	s_bcnt1_i32_b64 s99, s[100:101]
	s_cmp_ge_u32 s51, 16
	s_cselect_b32 s31, s52, s31
	s_cmp_ge_u32 s99, 16
	s_cselect_b32 s67, s98, s67
	s_cmp_eq_u32 s51, 16
	s_cselect_b32 s18, 1, s18
	s_cmp_eq_u32 s99, 16
	s_cselect_b32 s19, 1, s19
	s_and_b32 s20, s18, s19
	s_cbranch_scc1 .Ltk_fin
	s_or_b32 s52, s31, 4
	s_or_b32 s98, s67, 4
	v_cmp_le_u32_e32 vcc, s52, v34
	v_cmp_le_u32_e64 s[100:101], s98, v38
	s_bcnt1_i32_b64 s51, vcc
	s_bcnt1_i32_b64 s99, s[100:101]
	s_cmp_ge_u32 s51, 16
	s_cselect_b32 s31, s52, s31
	s_cmp_ge_u32 s99, 16
	s_cselect_b32 s67, s98, s67
	s_cmp_eq_u32 s51, 16
	s_cselect_b32 s18, 1, s18
	s_cmp_eq_u32 s99, 16
	s_cselect_b32 s19, 1, s19
	s_and_b32 s20, s18, s19
	s_cbranch_scc1 .Ltk_fin
	s_or_b32 s52, s31, 2
	s_or_b32 s98, s67, 2
	v_cmp_le_u32_e32 vcc, s52, v34
	v_cmp_le_u32_e64 s[100:101], s98, v38
	s_bcnt1_i32_b64 s51, vcc
	s_bcnt1_i32_b64 s99, s[100:101]
	s_cmp_ge_u32 s51, 16
	s_cselect_b32 s31, s52, s31
	s_cmp_ge_u32 s99, 16
	s_cselect_b32 s67, s98, s67
	s_cmp_eq_u32 s51, 16
	s_cselect_b32 s18, 1, s18
	s_cmp_eq_u32 s99, 16
	s_cselect_b32 s19, 1, s19
	s_and_b32 s20, s18, s19
	s_cbranch_scc1 .Ltk_fin
	s_or_b32 s52, s31, 1
	s_or_b32 s98, s67, 1
	v_cmp_le_u32_e32 vcc, s52, v34
	v_cmp_le_u32_e64 s[100:101], s98, v38
	s_bcnt1_i32_b64 s51, vcc
	s_bcnt1_i32_b64 s99, s[100:101]
	s_cmp_ge_u32 s51, 16
	s_cselect_b32 s31, s52, s31
	s_cmp_ge_u32 s99, 16
	s_cselect_b32 s67, s98, s67
.Ltk_fin:
	v_cmp_lt_u32_e32 vcc, s31, v34
	s_bcnt1_i32_b64 s51, vcc
	s_mov_b64 s[20:21], vcc
	v_cmp_eq_u32_e64 s[18:19], s31, v34
	s_sub_i32 s51, 16, s51
	s_nop 0
	v_mbcnt_lo_u32_b32 v35, s18, 0
	v_mbcnt_hi_u32_b32 v35, s19, v35
	v_cmp_gt_u32_e32 vcc, s51, v35
	s_and_b64 s[18:19], s[18:19], vcc
	s_or_b64 s[20:21], s[20:21], s[18:19]
	s_and_b64 s[20:21], s[20:21], s[16:17]
	v_cmp_lt_u32_e32 vcc, s67, v38
	s_bcnt1_i32_b64 s51, vcc
	s_mov_b64 s[100:101], vcc
	v_cmp_eq_u32_e64 s[18:19], s67, v38
	s_sub_i32 s51, 16, s51
	s_nop 0
	v_mbcnt_lo_u32_b32 v35, s18, 0
	v_mbcnt_hi_u32_b32 v35, s19, v35
	v_cmp_gt_u32_e32 vcc, s51, v35
	s_and_b64 s[18:19], s[18:19], vcc
	s_or_b64 s[100:101], s[100:101], s[18:19]
	s_and_b64 s[100:101], s[100:101], s[16:17]
	s_and_saveexec_b64 s[18:19], s[40:41]
	s_cbranch_execz .Ltk_latch
	s_lshl_b32 s30, s30, 3
	s_add_i32 s30, s30, 0x1c000
	v_mov_b32_e32 v0, s30
	v_mov_b64_e32 v[34:35], s[20:21]
	v_mov_b64_e32 v[38:39], s[100:101]
	ds_write_b64 v0, v[34:35]
	ds_write_b64 v0, v[38:39] offset:8
